# rwkv norm phase: previous-row loads issued together (temps renamed), counted vmcnt
# baseline (speedup 1.0000x reference)
; __device__ __forceinline__ unsigned pk2(float lo, float hi) { const f32x2 v = {lo, hi}; const hwbf16x2 b = __builtin_convertvector(v, hwbf16x2); return __builtin_bit_cast(unsigned, b); }
; __device__ __forceinline__ void norm_row(const float* hrow, const float* sh, const float* sc, int lane, f32x4 (&u)[4]) {
;     float ss = 0.f;
; #pragma unroll
;     for (int j = 0; j < 4; ++j) { u[j] = *(const f32x4*)(hrow + 4 * lane + 256 * j); ss += (u[j].x * u[j].x + u[j].y * u[j].y) + (u[j].z * u[j].z + u[j].w * u[j].w); }
;     ss = wave_sum(ss);
;     const float rstd = __builtin_amdgcn_rsqf(ss * (1.f / D) + 1e-6f);
; #pragma unroll
;     for (int j = 0; j < 4; ++j) { const f32x4 a = *(const f32x4*)(sc + 4 * lane + 256 * j), b = *(const f32x4*)(sh + 4 * lane + 256 * j);
;         u[j] = (u[j] * rstd) * (a + 1.0f) + b; }
; }
; __device__ __forceinline__ void norm_phase(const float* h, const float* modl  , int idx  , bf16* U, int mode, int tid) {
;     asm volatile("" : "+v"(tid));
;     const int lane = tid & 63, gw = blockIdx.x * 8 + (tid >> 6), NGW = gridDim.x * 8;
;     for (int row = gw; row < M; row += NGW) {
;         const int b = row >> 12, t = row & (SEQ - 1);
;         const float* sh = modl + (size_t)b * NMOD + (idx * 3) * D; const float* sc = sh + D;
;         f32x4 u[4]; norm_row(h + (size_t)row * D, sh, sc, lane, u);
;         if (mode == 0) {
; #pragma unroll
;             for (int j = 0; j < 4; ++j) { u32x2 o; o.x = pk2(u[j].x, u[j].y); o.y = pk2(u[j].z, u[j].w); *(u32x2*)(U + (size_t)row * D + 4 * lane + 256 * j) = o; }
;         } else {
;             f32x4 p[4];
;             if (t > 0) norm_row(h + (size_t)(row - 1) * D, sh, sc, lane, p);
;             else {
; #pragma unroll
;                 for (int j = 0; j < 4; ++j) p[j] = (f32x4){0.f, 0.f, 0.f, 0.f};
;             }
; #pragma unroll
;             for (int j = 0; j < 4; ++j) { u32x2 o; o.x = pk2(u[j].x, u[j].y); o.y = pk2(u[j].z, u[j].w); *(u32x2*)(U + (size_t)row * RW_K + 4 * lane + 256 * j) = o;
;                 const f32x4 x = p[j] - u[j]; u32x2 q; q.x = pk2(x.x, x.y); q.y = pk2(x.z, x.w); *(u32x2*)(U + (size_t)row * RW_K + D + 4 * lane + 256 * j) = q; }
.LBB0_1499:
	v_lshl_add_u64 v[12:13], v[42:43], 0, v[38:39]
	global_load_dwordx4 v[8:11], v[12:13], off
	global_load_dwordx4 v[4:7], v[12:13], off offset:1024
	global_load_dwordx4 v[0:3], v[12:13], off offset:3072
	s_nop 0
	global_load_dwordx4 v[12:15], v[12:13], off offset:2048
	v_ashrrev_i32_e32 v16, 12, v32
	v_mul_hi_i32_i24_e32 v17, 0x9000, v16
	v_mul_i32_i24_e32 v16, 0x9000, v16
	v_lshl_add_u64 v[16:17], s[2:3], 0, v[16:17]
	v_lshl_add_u64 v[16:17], v[16:17], 0, v[34:35]
	s_movk_i32 s10, 0x1000
	v_add_co_u32_e32 v18, vcc, s10, v16
	s_mov_b64 s[10:11], 0x1000
	s_nop 0
	v_addc_co_u32_e32 v19, vcc, 0, v17, vcc
	global_load_dwordx4 v[44:47], v[18:19], off
	v_lshl_add_u64 v[18:19], v[16:17], 0, s[10:11]
	global_load_dwordx4 v[48:51], v[18:19], off offset:1024
	global_load_dwordx4 v[64:67], v[18:19], off offset:2048
	global_load_dwordx4 v[76:79], v[18:19], off offset:3072
	global_load_dwordx4 v[28:31], v[16:17], off
	global_load_dwordx4 v[24:27], v[16:17], off offset:1024
	global_load_dwordx4 v[20:23], v[16:17], off offset:2048
	s_nop 0
	global_load_dwordx4 v[16:19], v[16:17], off offset:3072
	v_and_b32_e32 v63, 0xfff, v32
	v_cmp_ne_u32_e32 vcc, 0, v63
	v_mov_b32_e32 v74, 0
	v_mov_b32_e32 v75, 0
	s_waitcnt vmcnt(11)
	v_pk_mul_f32 v[52:53], v[10:11], v[10:11]
	v_pk_mul_f32 v[54:55], v[8:9], v[8:9]
	s_waitcnt vmcnt(10)
	v_pk_mul_f32 v[56:57], v[6:7], v[6:7]
	v_pk_mul_f32 v[58:59], v[4:5], v[4:5]
	v_pk_mov_b32 v[68:69], v[54:55], v[52:53] op_sel:[1,0]
	v_mov_b32_e32 v55, v53
	v_pk_mov_b32 v[52:53], v[58:59], v[56:57] op_sel:[1,0]
	v_mov_b32_e32 v59, v57
	s_waitcnt vmcnt(8)
	v_mul_f32_e32 v60, v13, v13
	v_mul_f32_e32 v62, v15, v15
	v_pk_add_f32 v[54:55], v[68:69], v[54:55]
	v_pk_add_f32 v[52:53], v[52:53], v[58:59]
	v_mul_f32_e32 v70, v0, v0
	v_mul_f32_e32 v71, v1, v1
	v_mul_f32_e32 v72, v2, v2
	v_mul_f32_e32 v73, v3, v3
	v_pk_fma_f32 v[56:57], v[12:13], v[12:13], v[60:61] op_sel_hi:[1,1,0]
	v_pk_fma_f32 v[60:61], v[14:15], v[14:15], v[62:63] op_sel_hi:[1,1,0]
	v_pk_add_f32 v[54:55], v[54:55], v[54:55] op_sel:[0,1] op_sel_hi:[1,0]
	v_pk_add_f32 v[52:53], v[52:53], v[52:53] op_sel:[0,1] op_sel_hi:[1,0]
	v_mov_b32_e32 v57, v72
	v_mov_b32_e32 v61, v73
	v_mov_b32_e32 v55, v70
	v_mov_b32_e32 v53, v71
	v_pk_add_f32 v[56:57], v[56:57], v[60:61]
	v_pk_add_f32 v[52:53], v[54:55], v[52:53]
	v_mov_b32_e32 v72, 0
	v_pk_add_f32 v[52:53], v[52:53], v[56:57]
	s_waitcnt vmcnt(7)
	v_pk_add_f32 v[56:57], v[46:47], 1.0 op_sel_hi:[1,0]
	v_add_f32_e32 v52, v52, v53
	ds_bpermute_b32 v53, v209, v52
	s_waitcnt vmcnt(4)
	v_pk_add_f32 v[46:47], v[76:77], 1.0 op_sel_hi:[1,0]
	v_mov_b32_e32 v73, 0
	v_mov_b32_e32 v68, 0
	v_mov_b32_e32 v69, 0
	s_waitcnt lgkmcnt(0)
	v_add_f32_e32 v52, v52, v53
	ds_bpermute_b32 v53, v210, v52
	v_mov_b32_e32 v70, 0
	v_mov_b32_e32 v71, 0
	v_mov_b32_e32 v60, 0
	v_mov_b32_e32 v61, 0
	s_waitcnt lgkmcnt(0)
	v_add_f32_e32 v52, v52, v53
	ds_bpermute_b32 v53, v211, v52
	v_mov_b32_e32 v62, 0
	v_pk_add_f32 v[58:59], v[44:45], 1.0 op_sel_hi:[1,0]
	v_pk_add_f32 v[54:55], v[48:49], 1.0 op_sel_hi:[1,0]
	v_pk_add_f32 v[48:49], v[66:67], 1.0 op_sel_hi:[1,0]
	s_waitcnt lgkmcnt(0)
	v_add_f32_e32 v63, v52, v53
	ds_bpermute_b32 v80, v212, v63
	v_pk_add_f32 v[52:53], v[50:51], 1.0 op_sel_hi:[1,0]
	v_pk_add_f32 v[50:51], v[64:65], 1.0 op_sel_hi:[1,0]
	v_pk_add_f32 v[44:45], v[78:79], 1.0 op_sel_hi:[1,0]
	v_mov_b32_e32 v64, 0
	s_waitcnt lgkmcnt(0)
	v_add_f32_e32 v63, v63, v80
	ds_bpermute_b32 v80, v207, v63
	v_mov_b32_e32 v65, 0
	v_mov_b32_e32 v66, 0
	v_mov_b32_e32 v67, 0
	s_waitcnt lgkmcnt(0)
	v_add_f32_e32 v76, v63, v80
	ds_bpermute_b32 v77, v208, v76
	v_mov_b32_e32 v63, 0
	s_and_saveexec_b64 s[10:11], vcc
	s_cbranch_execz .LBB0_1498
	v_add_u32_e32 v60, -1, v32
	v_ashrrev_i32_e32 v61, 31, v60
	v_lshlrev_b64 v[60:61], 12, v[60:61]
	v_lshl_add_u64 v[72:73], v[36:37], 0, v[60:61]
	global_load_dwordx4 v[60:63], v[72:73], off
	global_load_dwordx4 v[64:67], v[72:73], off offset:1024
	global_load_dwordx4 v[68:71], v[72:73], off offset:2048
	global_load_dwordx4 v[72:75], v[72:73], off offset:3072
	s_waitcnt vmcnt(3)
	v_pk_mul_f32 v[100:101], v[62:63], v[62:63]
	v_pk_mul_f32 v[102:103], v[60:61], v[60:61]
	s_nop 0
	v_pk_mov_b32 v[104:105], v[102:103], v[100:101] op_sel:[1,0]
	v_mov_b32_e32 v103, v101
	v_pk_add_f32 v[78:79], v[104:105], v[102:103]
	v_pk_add_f32 v[78:79], v[78:79], v[78:79] op_sel:[0,1] op_sel_hi:[1,0]
	s_waitcnt vmcnt(2)
	v_pk_mul_f32 v[106:107], v[66:67], v[66:67]
	v_pk_mul_f32 v[108:109], v[64:65], v[64:65]
	s_nop 0
	v_pk_mov_b32 v[110:111], v[108:109], v[106:107] op_sel:[1,0]
	v_mov_b32_e32 v109, v107
	v_pk_add_f32 v[80:81], v[110:111], v[108:109]
	s_nop 0
	v_pk_add_f32 v[80:81], v[80:81], v[80:81] op_sel:[0,1] op_sel_hi:[1,0]
	s_waitcnt vmcnt(0)
	v_mul_f32_e32 v82, v72, v72
	v_mul_f32_e32 v83, v73, v73
	v_mov_b32_e32 v79, v82
	v_mov_b32_e32 v81, v83
	v_pk_add_f32 v[78:79], v[78:79], v[80:81]
	v_mul_f32_e32 v80, v69, v69
	v_mul_f32_e32 v82, v71, v71
	v_mul_f32_e32 v84, v74, v74
	v_mul_f32_e32 v85, v75, v75
	v_pk_fma_f32 v[80:81], v[68:69], v[68:69], v[80:81] op_sel_hi:[1,1,0]
	v_pk_fma_f32 v[82:83], v[70:71], v[70:71], v[82:83] op_sel_hi:[1,1,0]
	v_mov_b32_e32 v81, v84
	v_mov_b32_e32 v83, v85
	v_pk_add_f32 v[80:81], v[80:81], v[82:83]
	s_nop 0
	v_pk_add_f32 v[78:79], v[78:79], v[80:81]
	s_nop 0
	v_add_f32_e32 v78, v78, v79
	ds_bpermute_b32 v79, v209, v78
	s_waitcnt lgkmcnt(0)
	v_add_f32_e32 v78, v78, v79
	ds_bpermute_b32 v79, v210, v78
	s_waitcnt lgkmcnt(0)
	v_add_f32_e32 v78, v78, v79
	ds_bpermute_b32 v79, v211, v78
	s_waitcnt lgkmcnt(0)
	v_add_f32_e32 v78, v78, v79
	ds_bpermute_b32 v79, v212, v78
	s_waitcnt lgkmcnt(0)
	v_add_f32_e32 v78, v78, v79
	ds_bpermute_b32 v79, v207, v78
	s_waitcnt lgkmcnt(0)
	v_add_f32_e32 v78, v78, v79
	ds_bpermute_b32 v79, v208, v78
	s_waitcnt lgkmcnt(0)
	v_add_f32_e32 v78, v78, v79
	v_fmamk_f32 v78, v78, 0x3a800000, v33
	v_rsq_f32_e32 v78, v78
	s_nop 0
	v_pk_mul_f32 v[80:81], v[60:61], v[78:79] op_sel_hi:[1,0]
	v_pk_mul_f32 v[82:83], v[62:63], v[78:79] op_sel_hi:[1,0]
	v_pk_mul_f32 v[84:85], v[64:65], v[78:79] op_sel_hi:[1,0]
	v_pk_mul_f32 v[86:87], v[66:67], v[78:79] op_sel_hi:[1,0]
	v_pk_mul_f32 v[60:61], v[68:69], v[78:79] op_sel_hi:[1,0]
	v_pk_mul_f32 v[62:63], v[70:71], v[78:79] op_sel_hi:[1,0]
	v_pk_mul_f32 v[64:65], v[72:73], v[78:79] op_sel_hi:[1,0]
	v_pk_mul_f32 v[66:67], v[74:75], v[78:79] op_sel_hi:[1,0]
	v_pk_fma_f32 v[64:65], v[46:47], v[64:65], v[16:17]
	v_pk_fma_f32 v[66:67], v[44:45], v[66:67], v[18:19]
	v_pk_fma_f32 v[62:63], v[48:49], v[62:63], v[22:23]
	v_pk_fma_f32 v[60:61], v[50:51], v[60:61], v[20:21]
	v_pk_fma_f32 v[70:71], v[52:53], v[86:87], v[26:27]
	v_pk_fma_f32 v[68:69], v[54:55], v[84:85], v[24:25]
	v_pk_fma_f32 v[74:75], v[56:57], v[82:83], v[30:31]
	v_pk_fma_f32 v[72:73], v[58:59], v[80:81], v[28:29]
	s_branch .LBB0_1498
